# also replace the m1->m2 grid barrier: per-A2-item arrive counter (sc1 state stores) + wait at m2 start
# baseline (speedup 1.0000x reference)
.LBB0_921:
	s_or_b64 exec, exec, s[26:27]
	v_readlane_b32 s6, v255, 16
	s_waitcnt lgkmcnt(0)
	s_barrier
	v_mul_hi_i32 v111, v106, s55
	s_waitcnt vmcnt(16)
	v_cndmask_b32_e64 v135, 0, v90, s[4:5]
	v_mov_b32_e32 v98, s6
	v_readlane_b32 s6, v255, 17
	ds_read_b32 v102, v98
	v_lshlrev_b32_e32 v90, 2, v110
	v_mov_b32_e32 v98, s6
	v_readlane_b32 s6, v255, 18
	ds_read_b32 v101, v98
	v_readlane_b32 s8, v255, 20
	v_mov_b32_e32 v98, s6
	v_readlane_b32 s6, v255, 19
	ds_read_b32 v98, v98
	s_waitcnt vmcnt(12)
	v_cndmask_b32_e32 v144, 0, v96, vcc
	v_mov_b32_e32 v100, s6
	ds_read_b32 v113, v100
	v_lshl_add_u32 v100, v109, 2, s45
	ds_read_b32 v100, v100 offset:1536
	s_movk_i32 s6, 0xf700
	v_add_u32_e32 v96, s8, v90
	v_cndmask_b32_e64 v141, 0, v92, s[4:5]
	v_cndmask_b32_e64 v142, 0, v93, s[4:5]
	s_waitcnt lgkmcnt(0)
	v_pk_add_f32 v[104:105], v[102:103], v[100:101] op_sel_hi:[0,1]
	v_sub_f32_e32 v100, v104, v105
	v_mul_f32_e32 v100, 0x3fb8aa3b, v100
	v_exp_f32_e32 v104, v100
	v_sub_u32_e32 v100, 0x67f, v109
	v_lshl_add_u32 v100, v100, 2, s45
	ds_read_b32 v112, v100
	v_cndmask_b32_e32 v136, 0, v94, vcc
	v_cndmask_b32_e32 v143, 0, v95, vcc
	v_cndmask_b32_e32 v145, 0, v97, vcc
	v_lshlrev_b32_e32 v134, 16, v136
	s_waitcnt lgkmcnt(0)
	v_pk_add_f32 v[100:101], v[98:99], v[112:113] op_sel_hi:[0,1]
	v_lshrrev_b32_e32 v112, 31, v111
	v_ashrrev_i32_e32 v111, 9, v111
	v_add_u32_e32 v111, v111, v112
	v_mov_b32_e32 v112, 0xffffff00
	v_mad_i32_i24 v138, v111, s6, v106
	v_lshlrev_b32_e32 v139, 8, v111
	v_lshl_add_u32 v140, v111, 11, v112
	ds_read_b128 v[92:95], v96
	ds_read_b128 v[110:113], v96 offset:16
	ds_read_b128 v[114:117], v96 offset:1536
	ds_read_b128 v[118:121], v96 offset:1552
	ds_read_b128 v[122:125], v96 offset:3072
	ds_read_b128 v[126:129], v96 offset:3088
	v_lshlrev_b32_e32 v96, 16, v135
	v_and_b32_e32 v97, 0xffff0000, v135
	v_and_b32_e32 v135, 0xffff0000, v136
	v_lshlrev_b32_e32 v136, 16, v86
	v_and_b32_e32 v137, 0xffff0000, v86
	s_waitcnt lgkmcnt(3)
	v_pk_mul_f32 v[114:115], v[114:115], v[136:137]
	v_cndmask_b32_e64 v91, 0, v91, s[4:5]
	v_pk_fma_f32 v[92:93], v[92:93], v[96:97], v[114:115]
	v_lshlrev_b32_e32 v114, 16, v143
	s_waitcnt lgkmcnt(1)
	v_pk_fma_f32 v[92:93], v[122:123], v[134:135], v[92:93]
	v_and_b32_e32 v115, 0xffff0000, v143
	v_mul_f32_e32 v86, 0xbfb8aa3b, v92
	v_exp_f32_e32 v86, v86
	v_cmp_lt_i32_e64 s[6:7], s54, v138
	v_sub_f32_e32 v100, v100, v101
	v_mul_f32_e32 v100, 0x3fb8aa3b, v100
	v_add_f32_e32 v86, 1.0, v86
	v_rcp_f32_e32 v96, v86
	v_mul_f32_e32 v86, 0xbfb8aa3b, v93
	v_exp_f32_e32 v86, v86
	v_exp_f32_e32 v100, v100
	v_mul_lo_u32 v109, v109, s46
	s_waitcnt vmcnt(0)
	v_cndmask_b32_e32 v123, 0, v82, vcc
	v_add_f32_e32 v86, 1.0, v86
	v_rcp_f32_e32 v97, v86
	v_lshlrev_b32_e32 v86, 16, v87
	v_and_b32_e32 v87, 0xffff0000, v87
	v_pk_mul_f32 v[86:87], v[116:117], v[86:87]
	v_pk_mul_f32 v[96:97], v[92:93], v[96:97]
	v_lshlrev_b32_e32 v92, 16, v91
	v_and_b32_e32 v93, 0xffff0000, v91
	v_pk_fma_f32 v[86:87], v[94:95], v[92:93], v[86:87]
	v_lshlrev_b32_e32 v94, 16, v88
	v_pk_fma_f32 v[86:87], v[124:125], v[114:115], v[86:87]
	v_and_b32_e32 v95, 0xffff0000, v88
	v_mul_f32_e32 v91, 0xbfb8aa3b, v86
	v_exp_f32_e32 v91, v91
	v_pk_mul_f32 v[94:95], v[118:119], v[94:95]
	v_cndmask_b32_e32 v134, 0, v84, vcc
	v_cndmask_b32_e32 v135, 0, v85, vcc
	v_add_f32_e32 v91, 1.0, v91
	v_rcp_f32_e32 v92, v91
	v_mul_f32_e32 v91, 0xbfb8aa3b, v87
	v_exp_f32_e32 v91, v91
	v_lshlrev_b32_e32 v124, 16, v74
	v_and_b32_e32 v125, 0xffff0000, v74
	v_lshlrev_b32_e32 v122, 16, v123
	v_add_f32_e32 v91, 1.0, v91
	v_rcp_f32_e32 v93, v91
	v_cndmask_b32_e64 v91, 0, v78, s[4:5]
	v_and_b32_e32 v123, 0xffff0000, v123
	v_lshlrev_b64 v[106:107], 10, v[106:107]
	v_pk_mul_f32 v[114:115], v[86:87], v[92:93]
	v_lshlrev_b32_e32 v86, 16, v141
	v_and_b32_e32 v87, 0xffff0000, v141
	v_lshlrev_b32_e32 v92, 16, v144
	v_and_b32_e32 v93, 0xffff0000, v144
	v_pk_fma_f32 v[86:87], v[110:111], v[86:87], v[94:95]
	v_lshl_add_u64 v[106:107], s[88:89], 0, v[106:107]
	s_waitcnt lgkmcnt(0)
	v_pk_fma_f32 v[86:87], v[126:127], v[92:93], v[86:87]
	v_cndmask_b32_e64 v126, 0, v79, s[4:5]
	v_mul_f32_e32 v88, 0xbfb8aa3b, v86
	v_exp_f32_e32 v88, v88
	v_cndmask_b32_e64 v127, 0, v80, s[4:5]
	v_lshl_add_u64 v[106:107], v[106:107], 0, s[40:41]
	v_and_b32_e32 v108, 15, v188
	v_add_f32_e32 v88, 1.0, v88
	v_rcp_f32_e32 v92, v88
	v_mul_f32_e32 v88, 0xbfb8aa3b, v87
	v_exp_f32_e32 v88, v88
	s_mov_b32 s26, s24
	s_mov_b32 s27, s24
	v_add_f32_e32 v88, 1.0, v88
	v_rcp_f32_e32 v93, v88
	v_lshlrev_b32_e32 v88, 16, v89
	v_and_b32_e32 v89, 0xffff0000, v89
	v_pk_mul_f32 v[88:89], v[120:121], v[88:89]
	v_pk_mul_f32 v[110:111], v[86:87], v[92:93]
	v_lshlrev_b32_e32 v86, 16, v142
	v_and_b32_e32 v87, 0xffff0000, v142
	v_lshlrev_b32_e32 v92, 16, v145
	v_and_b32_e32 v93, 0xffff0000, v145
	v_pk_fma_f32 v[86:87], v[112:113], v[86:87], v[88:89]
	v_cvt_pk_bf16_f32 v94, v110, v111
	v_pk_fma_f32 v[86:87], v[128:129], v[92:93], v[86:87]
	v_cvt_pk_bf16_f32 v92, v96, v97
	v_mul_f32_e32 v88, 0xbfb8aa3b, v86
	v_mul_f32_e32 v89, 0xbfb8aa3b, v87
	v_exp_f32_e32 v88, v88
	v_exp_f32_e32 v89, v89
	v_cvt_pk_bf16_f32 v93, v114, v115
	v_cndmask_b32_e64 v128, 0, v81, s[4:5]
	v_add_f32_e32 v88, 1.0, v88
	v_add_f32_e32 v89, 1.0, v89
	v_rcp_f32_e32 v88, v88
	v_rcp_f32_e32 v89, v89
	v_cndmask_b32_e32 v129, 0, v83, vcc
	v_pk_mul_f32 v[112:113], v[86:87], v[88:89]
	v_cndmask_b32_e64 v86, v139, v140, s[6:7]
	v_add_u32_e32 v86, v86, v138
	v_cndmask_b32_e64 v88, v214, v212, s[6:7]
	v_mov_b32_e32 v89, v1
	v_ashrrev_i32_e32 v87, 31, v86
	v_lshl_add_u64 v[88:89], s[78:79], 0, v[88:89]
	v_lshlrev_b64 v[86:87], 10, v[86:87]
	v_lshl_add_u64 v[86:87], v[88:89], 0, v[86:87]
	v_lshl_add_u64 v[86:87], v[86:87], 0, s[40:41]
	v_cvt_pk_bf16_f32 v95, v112, v113
	v_lshl_add_u64 v[86:87], v[86:87], 0, v[0:1]
	v_pk_mul_f32 v[88:89], v[104:105], v[96:97] op_sel_hi:[0,1]
	global_store_dwordx4 v[86:87], v[92:95], off
	v_readlane_b32 s6, v255, 21
	s_nop 0
	v_cvt_pk_bf16_f32 v92, v88, v89
	v_pk_mul_f32 v[88:89], v[104:105], v[114:115] op_sel_hi:[0,1]
	v_cvt_pk_bf16_f32 v93, v88, v89
	v_pk_mul_f32 v[88:89], v[104:105], v[110:111] op_sel_hi:[0,1]
	v_cvt_pk_bf16_f32 v94, v88, v89
	v_pk_mul_f32 v[88:89], v[104:105], v[112:113] op_sel_hi:[0,1]
	v_cvt_pk_bf16_f32 v95, v88, v89
	v_add3_u32 v88, 0, v109, v0
	ds_write_b128 v88, v[92:95]
	v_pk_mul_f32 v[92:93], v[100:101], v[96:97] op_sel_hi:[0,1]
	v_pk_mul_f32 v[94:95], v[100:101], v[114:115] op_sel_hi:[0,1]
	v_cvt_pk_bf16_f32 v92, v92, v93
	v_cvt_pk_bf16_f32 v93, v94, v95
	v_pk_mul_f32 v[94:95], v[100:101], v[110:111] op_sel_hi:[0,1]
	v_pk_mul_f32 v[96:97], v[100:101], v[112:113] op_sel_hi:[0,1]
	v_cvt_pk_bf16_f32 v94, v94, v95
	v_cvt_pk_bf16_f32 v95, v96, v97
	v_add3_u32 v89, s34, v109, v0
	ds_write_b128 v89, v[92:95]
	v_add_u32_e32 v96, s6, v90
	ds_read_b128 v[78:81], v96
	ds_read_b128 v[82:85], v96 offset:16
	ds_read_b128 v[92:95], v96 offset:1536
	ds_read_b128 v[110:113], v96 offset:1552
	ds_read_b128 v[114:117], v96 offset:3072
	ds_read_b128 v[118:121], v96 offset:3088
	v_lshlrev_b32_e32 v96, 16, v91
	v_and_b32_e32 v97, 0xffff0000, v91
	s_waitcnt lgkmcnt(3)
	v_pk_mul_f32 v[92:93], v[92:93], v[124:125]
	v_cndmask_b32_e64 v91, 0, v68, s[4:5]
	v_pk_fma_f32 v[78:79], v[78:79], v[96:97], v[92:93]
	v_lshlrev_b32_e32 v96, 16, v129
	s_waitcnt lgkmcnt(1)
	v_pk_fma_f32 v[78:79], v[114:115], v[122:123], v[78:79]
	v_and_b32_e32 v97, 0xffff0000, v129
	v_mul_f32_e32 v74, 0xbfb8aa3b, v78
	v_exp_f32_e32 v74, v74
	v_lshlrev_b32_e32 v114, 16, v62
	v_and_b32_e32 v115, 0xffff0000, v62
	v_lshlrev_b32_e32 v62, 16, v63
	v_add_f32_e32 v74, 1.0, v74
	v_rcp_f32_e32 v92, v74
	v_mul_f32_e32 v74, 0xbfb8aa3b, v79
	v_exp_f32_e32 v74, v74
	v_and_b32_e32 v63, 0xffff0000, v63
	v_add_f32_e32 v74, 1.0, v74
	v_rcp_f32_e32 v93, v74
	v_lshlrev_b32_e32 v74, 16, v75
	v_and_b32_e32 v75, 0xffff0000, v75
	v_pk_mul_f32 v[74:75], v[94:95], v[74:75]
	v_pk_mul_f32 v[78:79], v[78:79], v[92:93]
	v_lshlrev_b32_e32 v92, 16, v126
	v_and_b32_e32 v93, 0xffff0000, v126
	v_pk_fma_f32 v[74:75], v[80:81], v[92:93], v[74:75]
	v_lshlrev_b32_e32 v94, 16, v76
	v_pk_fma_f32 v[74:75], v[116:117], v[96:97], v[74:75]
	v_and_b32_e32 v95, 0xffff0000, v76
	v_mul_f32_e32 v80, 0xbfb8aa3b, v74
	v_mul_f32_e32 v81, 0xbfb8aa3b, v75
	v_exp_f32_e32 v80, v80
	v_exp_f32_e32 v81, v81
	v_pk_mul_f32 v[94:95], v[110:111], v[94:95]
	v_lshlrev_b32_e32 v92, 16, v134
	v_add_f32_e32 v80, 1.0, v80
	v_add_f32_e32 v81, 1.0, v81
	v_rcp_f32_e32 v80, v80
	v_rcp_f32_e32 v81, v81
	v_and_b32_e32 v93, 0xffff0000, v134
	v_cvt_pk_bf16_f32 v78, v78, v79
	v_cndmask_b32_e32 v116, 0, v71, vcc
	v_pk_mul_f32 v[74:75], v[74:75], v[80:81]
	v_lshlrev_b32_e32 v80, 16, v127
	v_and_b32_e32 v81, 0xffff0000, v127
	v_pk_fma_f32 v[80:81], v[82:83], v[80:81], v[94:95]
	v_cvt_pk_bf16_f32 v79, v74, v75
	s_waitcnt lgkmcnt(0)
	v_pk_fma_f32 v[80:81], v[118:119], v[92:93], v[80:81]
	v_lshlrev_b32_e32 v92, 16, v135
	v_mul_f32_e32 v76, 0xbfb8aa3b, v80
	v_exp_f32_e32 v76, v76
	v_and_b32_e32 v93, 0xffff0000, v135
	v_lshl_add_u64 v[74:75], v[106:107], 0, v[0:1]
	v_or_b32_e32 v119, 32, v90
	v_add_f32_e32 v76, 1.0, v76
	v_rcp_f32_e32 v82, v76
	v_mul_f32_e32 v76, 0xbfb8aa3b, v81
	v_exp_f32_e32 v76, v76
	v_add_u32_e32 v96, s8, v119
	v_cndmask_b32_e32 v107, 0, v70, vcc
	v_cndmask_b32_e32 v117, 0, v72, vcc
	v_add_f32_e32 v76, 1.0, v76
	v_rcp_f32_e32 v83, v76
	v_lshlrev_b32_e32 v76, 16, v77
	v_and_b32_e32 v77, 0xffff0000, v77
	v_pk_mul_f32 v[76:77], v[112:113], v[76:77]
	v_pk_mul_f32 v[80:81], v[80:81], v[82:83]
	v_lshlrev_b32_e32 v82, 16, v128
	v_and_b32_e32 v83, 0xffff0000, v128
	v_pk_fma_f32 v[76:77], v[84:85], v[82:83], v[76:77]
	v_cvt_pk_bf16_f32 v80, v80, v81
	v_pk_fma_f32 v[76:77], v[120:121], v[92:93], v[76:77]
	v_cndmask_b32_e32 v118, 0, v73, vcc
	v_mul_f32_e32 v82, 0xbfb8aa3b, v76
	v_mul_f32_e32 v83, 0xbfb8aa3b, v77
	v_exp_f32_e32 v82, v82
	v_exp_f32_e32 v83, v83
	v_lshlrev_b32_e32 v106, 16, v107
	v_and_b32_e32 v107, 0xffff0000, v107
	v_add_f32_e32 v82, 1.0, v82
	v_add_f32_e32 v83, 1.0, v83
	v_rcp_f32_e32 v82, v82
	v_rcp_f32_e32 v83, v83
	s_nop 0
	v_pk_mul_f32 v[76:77], v[76:77], v[82:83]
	s_nop 0
	v_cvt_pk_bf16_f32 v81, v76, v77
	v_add3_u32 v76, s35, v109, v0
	ds_write_b128 v76, v[78:81]
	global_store_dwordx4 v[74:75], v[78:81], off
	v_cndmask_b32_e64 v0, 0, v66, s[4:5]
	v_cndmask_b32_e64 v77, 0, v67, s[4:5]
	v_cndmask_b32_e64 v109, 0, v69, s[4:5]
	ds_read_b128 v[66:69], v96
	ds_read_b128 v[70:73], v96 offset:16
	ds_read_b128 v[78:81], v96 offset:1536
	ds_read_b128 v[82:85], v96 offset:1552
	ds_read_b128 v[92:95], v96 offset:3072
	ds_read_b128 v[110:113], v96 offset:3088
	v_lshlrev_b32_e32 v96, 16, v0
	v_and_b32_e32 v97, 0xffff0000, v0
	s_waitcnt lgkmcnt(3)
	v_pk_mul_f32 v[78:79], v[78:79], v[114:115]
	v_pk_mul_f32 v[62:63], v[80:81], v[62:63]
	v_pk_fma_f32 v[66:67], v[66:67], v[96:97], v[78:79]
	v_lshlrev_b32_e32 v80, 16, v64
	s_waitcnt lgkmcnt(1)
	v_pk_fma_f32 v[66:67], v[92:93], v[106:107], v[66:67]
	v_lshlrev_b32_e32 v92, 16, v116
	v_mul_f32_e32 v0, 0xbfb8aa3b, v66
	v_exp_f32_e32 v0, v0
	v_and_b32_e32 v93, 0xffff0000, v116
	v_and_b32_e32 v81, 0xffff0000, v64
	v_pk_mul_f32 v[80:81], v[82:83], v[80:81]
	v_add_f32_e32 v0, 1.0, v0
	v_rcp_f32_e32 v78, v0
	v_mul_f32_e32 v0, 0xbfb8aa3b, v67
	v_exp_f32_e32 v0, v0
	v_lshlrev_b32_e32 v64, 16, v65
	v_and_b32_e32 v65, 0xffff0000, v65
	v_pk_mul_f32 v[64:65], v[84:85], v[64:65]
	v_add_f32_e32 v0, 1.0, v0
	v_rcp_f32_e32 v79, v0
	v_cndmask_b32_e32 v85, 0, v58, vcc
	v_cndmask_b32_e32 v96, 0, v60, vcc
	v_cndmask_b32_e32 v97, 0, v61, vcc
	v_pk_mul_f32 v[66:67], v[66:67], v[78:79]
	v_lshlrev_b32_e32 v78, 16, v77
	v_and_b32_e32 v79, 0xffff0000, v77
	v_pk_fma_f32 v[62:63], v[68:69], v[78:79], v[62:63]
	v_lshlrev_b32_e32 v78, 16, v117
	v_pk_fma_f32 v[62:63], v[94:95], v[92:93], v[62:63]
	v_and_b32_e32 v79, 0xffff0000, v117
	v_mul_f32_e32 v0, 0xbfb8aa3b, v62
	v_exp_f32_e32 v0, v0
	v_cndmask_b32_e64 v77, 0, v55, s[4:5]
	v_cndmask_b32_e64 v94, 0, v57, s[4:5]
	v_cndmask_b32_e32 v95, 0, v59, vcc
	v_add_f32_e32 v0, 1.0, v0
	v_rcp_f32_e32 v68, v0
	v_mul_f32_e32 v0, 0xbfb8aa3b, v63
	v_exp_f32_e32 v0, v0
	v_lshlrev_b32_e32 v92, 16, v50
	v_and_b32_e32 v93, 0xffff0000, v50
	v_lshlrev_b32_e32 v84, 16, v85
	v_add_f32_e32 v0, 1.0, v0
	v_rcp_f32_e32 v69, v0
	v_and_b32_e32 v85, 0xffff0000, v85
	v_lshlrev_b32_e32 v50, 16, v51
	v_and_b32_e32 v51, 0xffff0000, v51
	v_pk_mul_f32 v[68:69], v[62:63], v[68:69]
	v_lshlrev_b32_e32 v62, 16, v91
	v_and_b32_e32 v63, 0xffff0000, v91
	v_pk_fma_f32 v[62:63], v[70:71], v[62:63], v[80:81]
	v_cndmask_b32_e64 v91, 0, v56, s[4:5]
	s_waitcnt lgkmcnt(0)
	v_pk_fma_f32 v[62:63], v[110:111], v[78:79], v[62:63]
	v_lshlrev_b32_e32 v78, 16, v118
	v_mul_f32_e32 v0, 0xbfb8aa3b, v62
	v_exp_f32_e32 v0, v0
	v_and_b32_e32 v79, 0xffff0000, v118
	v_add_f32_e32 v0, 1.0, v0
	v_rcp_f32_e32 v70, v0
	v_mul_f32_e32 v0, 0xbfb8aa3b, v63
	v_exp_f32_e32 v0, v0
	s_nop 0
	v_add_f32_e32 v0, 1.0, v0
	v_rcp_f32_e32 v71, v0
	s_nop 0
	v_pk_mul_f32 v[70:71], v[62:63], v[70:71]
	v_lshlrev_b32_e32 v62, 16, v109
	v_and_b32_e32 v63, 0xffff0000, v109
	v_pk_fma_f32 v[62:63], v[72:73], v[62:63], v[64:65]
	s_nop 0
	v_pk_fma_f32 v[62:63], v[112:113], v[78:79], v[62:63]
	s_nop 0
	v_mul_f32_e32 v0, 0xbfb8aa3b, v62
	v_exp_f32_e32 v0, v0
	s_nop 0
	v_add_f32_e32 v0, 1.0, v0
	v_rcp_f32_e32 v64, v0
	v_mul_f32_e32 v0, 0xbfb8aa3b, v63
	v_exp_f32_e32 v0, v0
	s_nop 0
	v_add_f32_e32 v0, 1.0, v0
	v_rcp_f32_e32 v65, v0
	v_cndmask_b32_e64 v0, 0, v54, s[4:5]
	v_lshlrev_b32_e32 v82, 16, v0
	v_and_b32_e32 v83, 0xffff0000, v0
	v_pk_mul_f32 v[72:73], v[62:63], v[64:65]
	v_cvt_pk_bf16_f32 v62, v66, v67
	v_cvt_pk_bf16_f32 v63, v68, v69
	v_cvt_pk_bf16_f32 v64, v70, v71
	v_cvt_pk_bf16_f32 v65, v72, v73
	global_store_dwordx4 v[86:87], v[62:65], off offset:16
	v_pk_mul_f32 v[78:79], v[104:105], v[72:73] op_sel_hi:[0,1]
	s_nop 0
	v_pk_mul_f32 v[62:63], v[104:105], v[66:67] op_sel_hi:[0,1]
	v_pk_mul_f32 v[64:65], v[104:105], v[68:69] op_sel_hi:[0,1]
	v_cvt_pk_bf16_f32 v62, v62, v63
	v_cvt_pk_bf16_f32 v63, v64, v65
	v_pk_mul_f32 v[64:65], v[104:105], v[70:71] op_sel_hi:[0,1]
	v_cvt_pk_bf16_f32 v64, v64, v65
	v_cvt_pk_bf16_f32 v65, v78, v79
	ds_write_b128 v88, v[62:65] offset:16
	v_pk_mul_f32 v[62:63], v[100:101], v[66:67] op_sel_hi:[0,1]
	v_pk_mul_f32 v[64:65], v[100:101], v[68:69] op_sel_hi:[0,1]
	v_cvt_pk_bf16_f32 v62, v62, v63
	v_cvt_pk_bf16_f32 v63, v64, v65
	v_pk_mul_f32 v[64:65], v[100:101], v[70:71] op_sel_hi:[0,1]
	v_pk_mul_f32 v[66:67], v[100:101], v[72:73] op_sel_hi:[0,1]
	v_cvt_pk_bf16_f32 v64, v64, v65
	v_cvt_pk_bf16_f32 v65, v66, v67
	ds_write_b128 v89, v[62:65] offset:16
	v_add_u32_e32 v78, s6, v119
	ds_read_b128 v[54:57], v78
	ds_read_b128 v[58:61], v78 offset:16
	ds_read_b128 v[62:65], v78 offset:1536
	ds_read_b128 v[66:69], v78 offset:1552
	ds_read_b128 v[70:73], v78 offset:3072
	ds_read_b128 v[78:81], v78 offset:3088
	s_waitcnt lgkmcnt(3)
	v_pk_mul_f32 v[62:63], v[62:63], v[92:93]
	s_nop 0
	v_pk_fma_f32 v[54:55], v[54:55], v[82:83], v[62:63]
	v_pk_mul_f32 v[50:51], v[64:65], v[50:51]
	s_waitcnt lgkmcnt(1)
	v_pk_fma_f32 v[54:55], v[70:71], v[84:85], v[54:55]
	v_lshlrev_b32_e32 v70, 16, v95
	v_mul_f32_e32 v0, 0xbfb8aa3b, v54
	v_exp_f32_e32 v0, v0
	v_and_b32_e32 v71, 0xffff0000, v95
	v_lshlrev_b32_e32 v64, 16, v52
	v_and_b32_e32 v65, 0xffff0000, v52
	v_add_f32_e32 v0, 1.0, v0
	v_rcp_f32_e32 v62, v0
	v_mul_f32_e32 v0, 0xbfb8aa3b, v55
	v_exp_f32_e32 v0, v0
	v_pk_mul_f32 v[64:65], v[66:67], v[64:65]
	v_lshlrev_b32_e32 v52, 16, v53
	v_and_b32_e32 v53, 0xffff0000, v53
	v_add_f32_e32 v0, 1.0, v0
	v_rcp_f32_e32 v63, v0
	v_pk_mul_f32 v[52:53], v[68:69], v[52:53]
	v_cndmask_b32_e32 v69, 0, v46, vcc
	v_lshlrev_b32_e32 v68, 16, v69
	v_pk_mul_f32 v[54:55], v[54:55], v[62:63]
	v_lshlrev_b32_e32 v62, 16, v77
	v_and_b32_e32 v63, 0xffff0000, v77
	v_pk_fma_f32 v[50:51], v[56:57], v[62:63], v[50:51]
	v_lshlrev_b32_e32 v62, 16, v96
	v_pk_fma_f32 v[50:51], v[72:73], v[70:71], v[50:51]
	v_and_b32_e32 v63, 0xffff0000, v96
	v_mul_f32_e32 v0, 0xbfb8aa3b, v50
	v_exp_f32_e32 v0, v0
	v_cndmask_b32_e64 v72, 0, v43, s[4:5]
	v_cndmask_b32_e64 v73, 0, v44, s[4:5]
	v_cndmask_b32_e64 v77, 0, v45, s[4:5]
	v_add_f32_e32 v0, 1.0, v0
	v_rcp_f32_e32 v56, v0
	v_mul_f32_e32 v0, 0xbfb8aa3b, v51
	v_exp_f32_e32 v0, v0
	v_lshlrev_b32_e32 v70, 16, v38
	v_and_b32_e32 v71, 0xffff0000, v38
	v_and_b32_e32 v69, 0xffff0000, v69
	v_add_f32_e32 v0, 1.0, v0
	v_rcp_f32_e32 v57, v0
	v_lshlrev_b32_e32 v38, 16, v39
	v_and_b32_e32 v39, 0xffff0000, v39
	v_pk_mul_f32 v[56:57], v[50:51], v[56:57]
	v_lshlrev_b32_e32 v50, 16, v91
	v_and_b32_e32 v51, 0xffff0000, v91
	v_pk_fma_f32 v[50:51], v[58:59], v[50:51], v[64:65]
	s_waitcnt lgkmcnt(0)
	v_pk_fma_f32 v[50:51], v[78:79], v[62:63], v[50:51]
	v_lshlrev_b32_e32 v62, 16, v97
	v_mul_f32_e32 v0, 0xbfb8aa3b, v50
	v_exp_f32_e32 v0, v0
	v_and_b32_e32 v63, 0xffff0000, v97
	v_cndmask_b32_e32 v78, 0, v47, vcc
	v_cndmask_b32_e32 v79, 0, v48, vcc
	v_add_f32_e32 v0, 1.0, v0
	v_rcp_f32_e32 v58, v0
	v_mul_f32_e32 v0, 0xbfb8aa3b, v51
	v_exp_f32_e32 v0, v0
	s_nop 0
	v_add_f32_e32 v0, 1.0, v0
	v_rcp_f32_e32 v59, v0
	s_nop 0
	v_pk_mul_f32 v[58:59], v[50:51], v[58:59]
	v_lshlrev_b32_e32 v50, 16, v94
	v_and_b32_e32 v51, 0xffff0000, v94
	v_pk_fma_f32 v[50:51], v[60:61], v[50:51], v[52:53]
	s_nop 0
	v_pk_fma_f32 v[50:51], v[80:81], v[62:63], v[50:51]
	v_or_b32_e32 v81, 64, v90
	v_mul_f32_e32 v0, 0xbfb8aa3b, v50
	v_exp_f32_e32 v0, v0
	v_add_u32_e32 v62, s8, v81
	v_cndmask_b32_e32 v80, 0, v49, vcc
	v_add_f32_e32 v0, 1.0, v0
	v_rcp_f32_e32 v52, v0
	v_mul_f32_e32 v0, 0xbfb8aa3b, v51
	v_exp_f32_e32 v0, v0
	s_nop 0
	v_add_f32_e32 v0, 1.0, v0
	v_rcp_f32_e32 v53, v0
	v_cndmask_b32_e64 v0, 0, v42, s[4:5]
	v_lshlrev_b32_e32 v66, 16, v0
	v_and_b32_e32 v67, 0xffff0000, v0
	v_pk_mul_f32 v[60:61], v[50:51], v[52:53]
	v_cvt_pk_bf16_f32 v50, v54, v55
	v_cvt_pk_bf16_f32 v51, v56, v57
	v_cvt_pk_bf16_f32 v52, v58, v59
	v_cvt_pk_bf16_f32 v53, v60, v61
	ds_write_b128 v76, v[50:53] offset:16
	global_store_dwordx4 v[74:75], v[50:53], off offset:16
	ds_read_b128 v[42:45], v62
	ds_read_b128 v[46:49], v62 offset:16
	ds_read_b128 v[50:53], v62 offset:1536
	ds_read_b128 v[54:57], v62 offset:1552
	ds_read_b128 v[58:61], v62 offset:3072
	ds_read_b128 v[62:65], v62 offset:3088
	s_waitcnt lgkmcnt(3)
	v_pk_mul_f32 v[50:51], v[50:51], v[70:71]
	s_nop 0
	v_pk_fma_f32 v[42:43], v[42:43], v[66:67], v[50:51]
	v_pk_mul_f32 v[38:39], v[52:53], v[38:39]
	s_waitcnt lgkmcnt(1)
	v_pk_fma_f32 v[42:43], v[58:59], v[68:69], v[42:43]
	v_lshlrev_b32_e32 v58, 16, v78
	v_mul_f32_e32 v0, 0xbfb8aa3b, v42
	v_exp_f32_e32 v0, v0
	v_and_b32_e32 v59, 0xffff0000, v78
	v_lshlrev_b32_e32 v52, 16, v40
	v_and_b32_e32 v53, 0xffff0000, v40
	v_add_f32_e32 v0, 1.0, v0
	v_rcp_f32_e32 v50, v0
	v_mul_f32_e32 v0, 0xbfb8aa3b, v43
	v_exp_f32_e32 v0, v0
	v_pk_mul_f32 v[52:53], v[54:55], v[52:53]
	v_lshlrev_b32_e32 v40, 16, v41
	v_and_b32_e32 v41, 0xffff0000, v41
	v_add_f32_e32 v0, 1.0, v0
	v_rcp_f32_e32 v51, v0
	v_pk_mul_f32 v[40:41], v[56:57], v[40:41]
	v_cndmask_b32_e32 v57, 0, v34, vcc
	v_lshlrev_b32_e32 v56, 16, v57
	v_pk_mul_f32 v[42:43], v[42:43], v[50:51]
	v_lshlrev_b32_e32 v50, 16, v72
	v_and_b32_e32 v51, 0xffff0000, v72
	v_pk_fma_f32 v[38:39], v[44:45], v[50:51], v[38:39]
	v_lshlrev_b32_e32 v50, 16, v79
	v_pk_fma_f32 v[38:39], v[60:61], v[58:59], v[38:39]
	v_and_b32_e32 v51, 0xffff0000, v79
	v_mul_f32_e32 v0, 0xbfb8aa3b, v38
	v_exp_f32_e32 v0, v0
	v_cndmask_b32_e64 v60, 0, v31, s[4:5]
	v_cndmask_b32_e64 v61, 0, v32, s[4:5]
	v_lshlrev_b32_e32 v58, 16, v26
	v_add_f32_e32 v0, 1.0, v0
	v_rcp_f32_e32 v44, v0
	v_mul_f32_e32 v0, 0xbfb8aa3b, v39
	v_exp_f32_e32 v0, v0
	v_and_b32_e32 v59, 0xffff0000, v26
	v_and_b32_e32 v57, 0xffff0000, v57
	v_lshlrev_b32_e32 v26, 16, v27
	v_add_f32_e32 v0, 1.0, v0
	v_rcp_f32_e32 v45, v0
	v_and_b32_e32 v27, 0xffff0000, v27
	v_pk_mul_f32 v[44:45], v[38:39], v[44:45]
	v_lshlrev_b32_e32 v38, 16, v73
	v_and_b32_e32 v39, 0xffff0000, v73
	v_pk_fma_f32 v[38:39], v[46:47], v[38:39], v[52:53]
	s_waitcnt lgkmcnt(0)
	v_pk_fma_f32 v[38:39], v[62:63], v[50:51], v[38:39]
	v_lshlrev_b32_e32 v50, 16, v80
	v_mul_f32_e32 v0, 0xbfb8aa3b, v38
	v_exp_f32_e32 v0, v0
	v_and_b32_e32 v51, 0xffff0000, v80
	v_cndmask_b32_e64 v62, 0, v33, s[4:5]
	v_cndmask_b32_e32 v63, 0, v35, vcc
	v_add_f32_e32 v0, 1.0, v0
	v_rcp_f32_e32 v46, v0
	v_mul_f32_e32 v0, 0xbfb8aa3b, v39
	v_exp_f32_e32 v0, v0
	s_nop 0
	v_add_f32_e32 v0, 1.0, v0
	v_rcp_f32_e32 v47, v0
	s_nop 0
	v_pk_mul_f32 v[46:47], v[38:39], v[46:47]
	v_lshlrev_b32_e32 v38, 16, v77
	v_and_b32_e32 v39, 0xffff0000, v77
	v_pk_fma_f32 v[38:39], v[48:49], v[38:39], v[40:41]
	s_nop 0
	v_pk_fma_f32 v[38:39], v[64:65], v[50:51], v[38:39]
	v_cndmask_b32_e32 v64, 0, v36, vcc
	v_mul_f32_e32 v0, 0xbfb8aa3b, v38
	v_exp_f32_e32 v0, v0
	v_cndmask_b32_e32 v65, 0, v37, vcc
	v_add_f32_e32 v0, 1.0, v0
	v_rcp_f32_e32 v40, v0
	v_mul_f32_e32 v0, 0xbfb8aa3b, v39
	v_exp_f32_e32 v0, v0
	s_nop 0
	v_add_f32_e32 v0, 1.0, v0
	v_rcp_f32_e32 v41, v0
	v_cndmask_b32_e64 v0, 0, v30, s[4:5]
	v_lshlrev_b32_e32 v54, 16, v0
	v_and_b32_e32 v55, 0xffff0000, v0
	v_pk_mul_f32 v[48:49], v[38:39], v[40:41]
	v_cvt_pk_bf16_f32 v38, v42, v43
	v_cvt_pk_bf16_f32 v39, v44, v45
	v_cvt_pk_bf16_f32 v40, v46, v47
	v_cvt_pk_bf16_f32 v41, v48, v49
	global_store_dwordx4 v[86:87], v[38:41], off offset:32
	v_pk_mul_f32 v[50:51], v[104:105], v[48:49] op_sel_hi:[0,1]
	s_nop 0
	v_pk_mul_f32 v[38:39], v[104:105], v[42:43] op_sel_hi:[0,1]
	v_pk_mul_f32 v[40:41], v[104:105], v[44:45] op_sel_hi:[0,1]
	v_cvt_pk_bf16_f32 v38, v38, v39
	v_cvt_pk_bf16_f32 v39, v40, v41
	v_pk_mul_f32 v[40:41], v[104:105], v[46:47] op_sel_hi:[0,1]
	v_cvt_pk_bf16_f32 v40, v40, v41
	v_cvt_pk_bf16_f32 v41, v50, v51
	ds_write_b128 v88, v[38:41] offset:32
	v_pk_mul_f32 v[38:39], v[100:101], v[42:43] op_sel_hi:[0,1]
	v_pk_mul_f32 v[40:41], v[100:101], v[44:45] op_sel_hi:[0,1]
	v_cvt_pk_bf16_f32 v38, v38, v39
	v_cvt_pk_bf16_f32 v39, v40, v41
	v_pk_mul_f32 v[40:41], v[100:101], v[46:47] op_sel_hi:[0,1]
	v_pk_mul_f32 v[42:43], v[100:101], v[48:49] op_sel_hi:[0,1]
	v_cvt_pk_bf16_f32 v40, v40, v41
	v_cvt_pk_bf16_f32 v41, v42, v43
	ds_write_b128 v89, v[38:41] offset:32
	v_add_u32_e32 v50, s6, v81
	ds_read_b128 v[30:33], v50
	ds_read_b128 v[34:37], v50 offset:16
	ds_read_b128 v[38:41], v50 offset:1536
	ds_read_b128 v[42:45], v50 offset:1552
	ds_read_b128 v[46:49], v50 offset:3072
	ds_read_b128 v[50:53], v50 offset:3088
	s_waitcnt lgkmcnt(3)
	v_pk_mul_f32 v[38:39], v[38:39], v[58:59]
	s_nop 0
	v_pk_fma_f32 v[30:31], v[30:31], v[54:55], v[38:39]
	v_pk_mul_f32 v[26:27], v[40:41], v[26:27]
	s_waitcnt lgkmcnt(1)
	v_pk_fma_f32 v[30:31], v[46:47], v[56:57], v[30:31]
	v_lshlrev_b32_e32 v46, 16, v63
	v_mul_f32_e32 v0, 0xbfb8aa3b, v30
	v_exp_f32_e32 v0, v0
	v_and_b32_e32 v47, 0xffff0000, v63
	v_lshlrev_b32_e32 v40, 16, v28
	v_and_b32_e32 v41, 0xffff0000, v28
	v_add_f32_e32 v0, 1.0, v0
	v_rcp_f32_e32 v38, v0
	v_mul_f32_e32 v0, 0xbfb8aa3b, v31
	v_exp_f32_e32 v0, v0
	v_pk_mul_f32 v[40:41], v[42:43], v[40:41]
	v_lshlrev_b32_e32 v28, 16, v29
	v_and_b32_e32 v29, 0xffff0000, v29
	v_add_f32_e32 v0, 1.0, v0
	v_rcp_f32_e32 v39, v0
	v_pk_mul_f32 v[28:29], v[44:45], v[28:29]
	v_or_b32_e32 v54, 0x60, v90
	v_cndmask_b32_e32 v45, 0, v22, vcc
	v_pk_mul_f32 v[30:31], v[30:31], v[38:39]
	v_lshlrev_b32_e32 v38, 16, v60
	v_and_b32_e32 v39, 0xffff0000, v60
	v_pk_fma_f32 v[26:27], v[32:33], v[38:39], v[26:27]
	v_lshlrev_b32_e32 v38, 16, v64
	v_pk_fma_f32 v[26:27], v[48:49], v[46:47], v[26:27]
	v_and_b32_e32 v39, 0xffff0000, v64
	v_mul_f32_e32 v0, 0xbfb8aa3b, v26
	v_exp_f32_e32 v0, v0
	v_cndmask_b32_e64 v48, 0, v19, s[4:5]
	v_cndmask_b32_e64 v49, 0, v20, s[4:5]
	v_lshlrev_b32_e32 v46, 16, v14
	v_add_f32_e32 v0, 1.0, v0
	v_rcp_f32_e32 v32, v0
	v_mul_f32_e32 v0, 0xbfb8aa3b, v27
	v_exp_f32_e32 v0, v0
	v_and_b32_e32 v47, 0xffff0000, v14
	v_lshlrev_b32_e32 v44, 16, v45
	v_and_b32_e32 v45, 0xffff0000, v45
	v_add_f32_e32 v0, 1.0, v0
	v_rcp_f32_e32 v33, v0
	v_lshlrev_b32_e32 v14, 16, v15
	v_and_b32_e32 v15, 0xffff0000, v15
	v_pk_mul_f32 v[32:33], v[26:27], v[32:33]
	v_lshlrev_b32_e32 v26, 16, v61
	v_and_b32_e32 v27, 0xffff0000, v61
	v_pk_fma_f32 v[26:27], v[34:35], v[26:27], v[40:41]
	s_waitcnt lgkmcnt(0)
	v_pk_fma_f32 v[26:27], v[50:51], v[38:39], v[26:27]
	v_lshlrev_b32_e32 v38, 16, v65
	v_mul_f32_e32 v0, 0xbfb8aa3b, v26
	v_exp_f32_e32 v0, v0
	v_and_b32_e32 v39, 0xffff0000, v65
	v_cndmask_b32_e64 v50, 0, v21, s[4:5]
	v_cndmask_b32_e32 v51, 0, v23, vcc
	v_add_f32_e32 v0, 1.0, v0
	v_rcp_f32_e32 v34, v0
	v_mul_f32_e32 v0, 0xbfb8aa3b, v27
	v_exp_f32_e32 v0, v0
	s_nop 0
	v_add_f32_e32 v0, 1.0, v0
	v_rcp_f32_e32 v35, v0
	s_nop 0
	v_pk_mul_f32 v[34:35], v[26:27], v[34:35]
	v_lshlrev_b32_e32 v26, 16, v62
	v_and_b32_e32 v27, 0xffff0000, v62
	v_pk_fma_f32 v[26:27], v[36:37], v[26:27], v[28:29]
	s_nop 0
	v_pk_fma_f32 v[26:27], v[52:53], v[38:39], v[26:27]
	v_add_u32_e32 v38, s8, v54
	v_mul_f32_e32 v0, 0xbfb8aa3b, v26
	v_exp_f32_e32 v0, v0
	v_cndmask_b32_e32 v52, 0, v24, vcc
	v_cndmask_b32_e32 v53, 0, v25, vcc
	v_add_f32_e32 v0, 1.0, v0
	v_rcp_f32_e32 v28, v0
	v_mul_f32_e32 v0, 0xbfb8aa3b, v27
	v_exp_f32_e32 v0, v0
	s_nop 0
	v_add_f32_e32 v0, 1.0, v0
	v_rcp_f32_e32 v29, v0
	v_cndmask_b32_e64 v0, 0, v18, s[4:5]
	v_lshlrev_b32_e32 v42, 16, v0
	v_and_b32_e32 v43, 0xffff0000, v0
	v_pk_mul_f32 v[36:37], v[26:27], v[28:29]
	v_cvt_pk_bf16_f32 v26, v30, v31
	v_cvt_pk_bf16_f32 v27, v32, v33
	v_cvt_pk_bf16_f32 v28, v34, v35
	v_cvt_pk_bf16_f32 v29, v36, v37
	ds_write_b128 v76, v[26:29] offset:32
	global_store_dwordx4 v[74:75], v[26:29], off offset:32
	ds_read_b128 v[18:21], v38
	ds_read_b128 v[22:25], v38 offset:16
	ds_read_b128 v[26:29], v38 offset:1536
	ds_read_b128 v[30:33], v38 offset:1552
	ds_read_b128 v[34:37], v38 offset:3072
	ds_read_b128 v[38:41], v38 offset:3088
	s_waitcnt lgkmcnt(3)
	v_pk_mul_f32 v[26:27], v[26:27], v[46:47]
	s_nop 0
	v_pk_fma_f32 v[18:19], v[18:19], v[42:43], v[26:27]
	v_pk_mul_f32 v[14:15], v[28:29], v[14:15]
	s_waitcnt lgkmcnt(1)
	v_pk_fma_f32 v[18:19], v[34:35], v[44:45], v[18:19]
	v_lshlrev_b32_e32 v34, 16, v51
	v_mul_f32_e32 v0, 0xbfb8aa3b, v18
	v_exp_f32_e32 v0, v0
	v_and_b32_e32 v35, 0xffff0000, v51
	v_lshlrev_b32_e32 v28, 16, v16
	v_and_b32_e32 v29, 0xffff0000, v16
	v_add_f32_e32 v0, 1.0, v0
	v_rcp_f32_e32 v26, v0
	v_mul_f32_e32 v0, 0xbfb8aa3b, v19
	v_exp_f32_e32 v0, v0
	v_pk_mul_f32 v[28:29], v[30:31], v[28:29]
	v_lshlrev_b32_e32 v16, 16, v17
	v_and_b32_e32 v17, 0xffff0000, v17
	v_add_f32_e32 v0, 1.0, v0
	v_rcp_f32_e32 v27, v0
	v_pk_mul_f32 v[16:17], v[32:33], v[16:17]
	v_cndmask_b32_e32 v33, 0, v10, vcc
	v_lshlrev_b32_e32 v32, 16, v33
	v_pk_mul_f32 v[18:19], v[18:19], v[26:27]
	v_lshlrev_b32_e32 v26, 16, v48
	v_and_b32_e32 v27, 0xffff0000, v48
	v_pk_fma_f32 v[14:15], v[20:21], v[26:27], v[14:15]
	v_lshlrev_b32_e32 v26, 16, v52
	v_pk_fma_f32 v[14:15], v[36:37], v[34:35], v[14:15]
	v_and_b32_e32 v27, 0xffff0000, v52
	v_mul_f32_e32 v0, 0xbfb8aa3b, v14
	v_exp_f32_e32 v0, v0
	v_cndmask_b32_e64 v36, 0, v7, s[4:5]
	v_cndmask_b32_e64 v37, 0, v8, s[4:5]
	v_lshlrev_b32_e32 v34, 16, v2
	v_add_f32_e32 v0, 1.0, v0
	v_rcp_f32_e32 v20, v0
	v_mul_f32_e32 v0, 0xbfb8aa3b, v15
	v_exp_f32_e32 v0, v0
	v_and_b32_e32 v35, 0xffff0000, v2
	v_and_b32_e32 v33, 0xffff0000, v33
	v_lshlrev_b32_e32 v2, 16, v3
	v_add_f32_e32 v0, 1.0, v0
	v_rcp_f32_e32 v21, v0
	v_and_b32_e32 v3, 0xffff0000, v3
	v_pk_mul_f32 v[20:21], v[14:15], v[20:21]
	v_lshlrev_b32_e32 v14, 16, v49
	v_and_b32_e32 v15, 0xffff0000, v49
	v_pk_fma_f32 v[14:15], v[22:23], v[14:15], v[28:29]
	s_waitcnt lgkmcnt(0)
	v_pk_fma_f32 v[14:15], v[38:39], v[26:27], v[14:15]
	v_lshlrev_b32_e32 v26, 16, v53
	v_mul_f32_e32 v0, 0xbfb8aa3b, v14
	v_exp_f32_e32 v0, v0
	v_and_b32_e32 v27, 0xffff0000, v53
	v_cndmask_b32_e64 v38, 0, v9, s[4:5]
	v_cndmask_b32_e32 v39, 0, v11, vcc
	v_add_f32_e32 v0, 1.0, v0
	v_rcp_f32_e32 v22, v0
	v_mul_f32_e32 v0, 0xbfb8aa3b, v15
	v_exp_f32_e32 v0, v0
	s_nop 0
	v_add_f32_e32 v0, 1.0, v0
	v_rcp_f32_e32 v23, v0
	s_nop 0
	v_pk_mul_f32 v[22:23], v[14:15], v[22:23]
	v_lshlrev_b32_e32 v14, 16, v50
	v_and_b32_e32 v15, 0xffff0000, v50
	v_pk_fma_f32 v[14:15], v[24:25], v[14:15], v[16:17]
	s_nop 0
	v_pk_fma_f32 v[14:15], v[40:41], v[26:27], v[14:15]
	v_cndmask_b32_e32 v40, 0, v12, vcc
	v_mul_f32_e32 v0, 0xbfb8aa3b, v14
	v_exp_f32_e32 v0, v0
	v_cndmask_b32_e32 v41, 0, v13, vcc
	v_cmp_eq_u32_e32 vcc, 0, v108
	v_add_f32_e32 v0, 1.0, v0
	v_rcp_f32_e32 v16, v0
	v_mul_f32_e32 v0, 0xbfb8aa3b, v15
	v_exp_f32_e32 v0, v0
	s_nop 0
	v_add_f32_e32 v0, 1.0, v0
	v_rcp_f32_e32 v17, v0
	v_cndmask_b32_e64 v0, 0, v6, s[4:5]
	v_lshlrev_b32_e32 v30, 16, v0
	v_and_b32_e32 v31, 0xffff0000, v0
	v_pk_mul_f32 v[24:25], v[14:15], v[16:17]
	v_cvt_pk_bf16_f32 v14, v18, v19
	v_cvt_pk_bf16_f32 v15, v20, v21
	v_cvt_pk_bf16_f32 v16, v22, v23
	v_cvt_pk_bf16_f32 v17, v24, v25
	global_store_dwordx4 v[86:87], v[14:17], off offset:48
	v_pk_mul_f32 v[26:27], v[104:105], v[24:25] op_sel_hi:[0,1]
	s_lshl_b32 s4, s31, 3
	v_pk_mul_f32 v[14:15], v[104:105], v[18:19] op_sel_hi:[0,1]
	v_pk_mul_f32 v[16:17], v[104:105], v[20:21] op_sel_hi:[0,1]
	v_cvt_pk_bf16_f32 v14, v14, v15
	v_cvt_pk_bf16_f32 v15, v16, v17
	v_pk_mul_f32 v[16:17], v[104:105], v[22:23] op_sel_hi:[0,1]
	v_cvt_pk_bf16_f32 v16, v16, v17
	v_cvt_pk_bf16_f32 v17, v26, v27
	ds_write_b128 v88, v[14:17] offset:48
	v_pk_mul_f32 v[14:15], v[100:101], v[18:19] op_sel_hi:[0,1]
	v_pk_mul_f32 v[16:17], v[100:101], v[20:21] op_sel_hi:[0,1]
	v_cvt_pk_bf16_f32 v14, v14, v15
	v_cvt_pk_bf16_f32 v15, v16, v17
	v_pk_mul_f32 v[16:17], v[100:101], v[22:23] op_sel_hi:[0,1]
	v_pk_mul_f32 v[18:19], v[100:101], v[24:25] op_sel_hi:[0,1]
	v_cvt_pk_bf16_f32 v16, v16, v17
	v_cvt_pk_bf16_f32 v17, v18, v19
	ds_write_b128 v89, v[14:17] offset:48
	v_add_u32_e32 v26, s6, v54
	ds_read_b128 v[6:9], v26
	ds_read_b128 v[10:13], v26 offset:16
	ds_read_b128 v[14:17], v26 offset:1536
	ds_read_b128 v[18:21], v26 offset:1552
	ds_read_b128 v[22:25], v26 offset:3072
	ds_read_b128 v[26:29], v26 offset:3088
	s_or_b32 s10, s4, s25
	s_waitcnt lgkmcnt(3)
	v_pk_mul_f32 v[14:15], v[14:15], v[34:35]
	v_pk_mul_f32 v[2:3], v[16:17], v[2:3]
	v_pk_fma_f32 v[6:7], v[6:7], v[30:31], v[14:15]
	v_lshlrev_b32_e32 v16, 16, v4
	s_waitcnt lgkmcnt(1)
	v_pk_fma_f32 v[6:7], v[22:23], v[32:33], v[6:7]
	v_lshlrev_b32_e32 v22, 16, v39
	v_mul_f32_e32 v0, 0xbfb8aa3b, v6
	v_exp_f32_e32 v0, v0
	v_and_b32_e32 v23, 0xffff0000, v39
	v_and_b32_e32 v17, 0xffff0000, v4
	v_pk_mul_f32 v[16:17], v[18:19], v[16:17]
	v_add_f32_e32 v0, 1.0, v0
	v_rcp_f32_e32 v14, v0
	v_mul_f32_e32 v0, 0xbfb8aa3b, v7
	v_exp_f32_e32 v0, v0
	v_lshlrev_b32_e32 v4, 16, v5
	v_and_b32_e32 v5, 0xffff0000, v5
	v_pk_mul_f32 v[4:5], v[20:21], v[4:5]
	v_add_f32_e32 v0, 1.0, v0
	v_rcp_f32_e32 v15, v0
	v_lshlrev_b32_e32 v18, 4, v103
	v_or_b32_e32 v20, v18, v108
	v_ashrrev_i32_e32 v21, 31, v20
	v_pk_mul_f32 v[6:7], v[6:7], v[14:15]
	v_lshlrev_b32_e32 v14, 16, v36
	v_and_b32_e32 v15, 0xffff0000, v36
	v_pk_fma_f32 v[2:3], v[8:9], v[14:15], v[2:3]
	v_lshlrev_b32_e32 v14, 16, v40
	v_pk_fma_f32 v[2:3], v[24:25], v[22:23], v[2:3]
	v_and_b32_e32 v15, 0xffff0000, v40
	v_mul_f32_e32 v0, 0xbfb8aa3b, v2
	v_exp_f32_e32 v0, v0
	v_lshlrev_b64 v[20:21], 8, v[20:21]
	v_lshl_add_u64 v[20:21], s[90:91], 0, v[20:21]
	v_ashrrev_i32_e32 v19, 31, v18
	v_add_f32_e32 v0, 1.0, v0
	v_rcp_f32_e32 v8, v0
	v_mul_f32_e32 v0, 0xbfb8aa3b, v3
	v_exp_f32_e32 v0, v0
	v_lshl_add_u64 v[18:19], v[18:19], 2, s[52:53]
	s_mul_i32 s10, s10, 18
	s_add_i32 s6, s10, s30
	v_add_f32_e32 v0, 1.0, v0
	v_rcp_f32_e32 v9, v0
	s_ashr_i32 s7, s6, 31
	s_lshl_b64 s[4:5], s[6:7], 15
	s_mov_b32 s25, s24
	v_pk_mul_f32 v[8:9], v[2:3], v[8:9]
	v_lshlrev_b32_e32 v2, 16, v37
	v_and_b32_e32 v3, 0xffff0000, v37
	v_pk_fma_f32 v[2:3], v[10:11], v[2:3], v[16:17]
	s_waitcnt lgkmcnt(0)
	v_pk_fma_f32 v[2:3], v[26:27], v[14:15], v[2:3]
	v_lshlrev_b32_e32 v14, 16, v41
	v_mul_f32_e32 v0, 0xbfb8aa3b, v2
	v_exp_f32_e32 v0, v0
	v_and_b32_e32 v15, 0xffff0000, v41
	v_lshlrev_b32_e32 v26, 5, v103
	v_add_f32_e32 v0, 1.0, v0
	v_rcp_f32_e32 v10, v0
	v_mul_f32_e32 v0, 0xbfb8aa3b, v3
	v_exp_f32_e32 v0, v0
	s_nop 0
	v_add_f32_e32 v0, 1.0, v0
	v_rcp_f32_e32 v11, v0
	s_nop 0
	v_pk_mul_f32 v[10:11], v[2:3], v[10:11]
	v_lshlrev_b32_e32 v2, 16, v38
	v_and_b32_e32 v3, 0xffff0000, v38
	v_pk_fma_f32 v[2:3], v[12:13], v[2:3], v[4:5]
	s_nop 0
	v_pk_fma_f32 v[2:3], v[28:29], v[14:15], v[2:3]
	s_nop 0
	v_mul_f32_e32 v0, 0xbfb8aa3b, v2
	v_exp_f32_e32 v0, v0
	s_nop 0
	v_add_f32_e32 v0, 1.0, v0
	v_rcp_f32_e32 v4, v0
	v_mul_f32_e32 v0, 0xbfb8aa3b, v3
	v_exp_f32_e32 v0, v0
	s_nop 0
	v_add_f32_e32 v0, 1.0, v0
	v_rcp_f32_e32 v5, v0
	v_lshrrev_b32_e32 v0, 1, v99
	v_and_b32_e32 v0, 24, v0
	v_lshl_add_u64 v[24:25], v[20:21], 0, v[0:1]
	v_pk_mul_f32 v[12:13], v[2:3], v[4:5]
	v_cvt_pk_bf16_f32 v2, v6, v7
	v_cvt_pk_bf16_f32 v3, v8, v9
	v_cvt_pk_bf16_f32 v4, v10, v11
	v_cvt_pk_bf16_f32 v5, v12, v13
	ds_write_b128 v76, v[2:5] offset:48
	global_store_dwordx4 v[74:75], v[2:5], off offset:48
	s_waitcnt lgkmcnt(0)
	s_barrier
	s_nop 1
	v_bfe_u32 v2, v188, 2, 2
	v_lshlrev_b32_e32 v4, 2, v188
	v_or_b32_e32 v2, v0, v2
	v_and_b32_e32 v4, 12, v4
	v_add_u32_e32 v3, s35, v26
	v_lshlrev_b32_e32 v27, 1, v4
	v_mul_u32_u24_e32 v28, 0x110, v2
	v_add3_u32 v16, v3, v27, v28
	v_and_b32_e32 v0, 48, v99
	ds_read_b64_tr_b16 v[2:3], v16
	ds_read_b64_tr_b16 v[4:5], v16 offset:1088
	ds_read_b64_tr_b16 v[6:7], v16 offset:8704
	ds_read_b64_tr_b16 v[8:9], v16 offset:9792
	ds_read_b64_tr_b16 v[10:11], v16 offset:17408
	ds_read_b64_tr_b16 v[12:13], v16 offset:18496
	ds_read_b64_tr_b16 v[14:15], v16 offset:26112
	ds_read_b64_tr_b16 v[16:17], v16 offset:27200
	v_lshl_add_u64 v[22:23], v[18:19], 0, v[0:1]
	v_add3_u32 v0, 0, v27, v28
	ds_read_b64_tr_b16 v[30:31], v0
	ds_read_b64_tr_b16 v[32:33], v0 offset:1088
	ds_read_b64_tr_b16 v[34:35], v0 offset:8704
	ds_read_b64_tr_b16 v[36:37], v0 offset:9792
	ds_read_b64_tr_b16 v[166:167], v0 offset:17408
	ds_read_b64_tr_b16 v[168:169], v0 offset:18496
	ds_read_b64_tr_b16 v[170:171], v0 offset:26112
	ds_read_b64_tr_b16 v[172:173], v0 offset:27200
	v_lshl_add_u64 v[18:19], v[24:25], 0, s[4:5]
	s_waitcnt lgkmcnt(6)
	v_mfma_f32_16x16x32_bf16 v[30:33], v[30:33], v[2:5], 0
	s_waitcnt lgkmcnt(4)
	v_mfma_f32_16x16x32_bf16 v[30:33], v[34:37], v[6:9], v[30:33]
	s_waitcnt lgkmcnt(2)
	v_mfma_f32_16x16x32_bf16 v[30:33], v[166:169], v[10:13], v[30:33]
	s_waitcnt lgkmcnt(0)
	v_mfma_f32_16x16x32_bf16 v[30:33], v[170:173], v[14:17], v[30:33]
	ds_read_b64_tr_b16 v[150:151], v0 offset:32
	ds_read_b64_tr_b16 v[152:153], v0 offset:1120
	ds_read_b64_tr_b16 v[154:155], v0 offset:8736
	ds_read_b64_tr_b16 v[156:157], v0 offset:9824
	ds_read_b64_tr_b16 v[158:159], v0 offset:17440
	ds_read_b64_tr_b16 v[160:161], v0 offset:18528
	ds_read_b64_tr_b16 v[162:163], v0 offset:26144
	ds_read_b64_tr_b16 v[164:165], v0 offset:27232
	s_nop 1
	v_cvt_pk_bf16_f32 v20, v30, v31
	v_cvt_pk_bf16_f32 v21, v32, v33
	global_store_dwordx2 v[18:19], v[20:21], off sc1
	s_waitcnt lgkmcnt(6)
	v_mfma_f32_16x16x32_bf16 v[150:153], v[150:153], v[2:5], 0
	s_waitcnt lgkmcnt(4)
	v_mfma_f32_16x16x32_bf16 v[150:153], v[154:157], v[6:9], v[150:153]
	s_waitcnt lgkmcnt(2)
	v_mfma_f32_16x16x32_bf16 v[150:153], v[158:161], v[10:13], v[150:153]
	s_waitcnt lgkmcnt(0)
	v_mfma_f32_16x16x32_bf16 v[150:153], v[162:165], v[14:17], v[150:153]
	ds_read_b64_tr_b16 v[30:31], v0 offset:64
	ds_read_b64_tr_b16 v[32:33], v0 offset:1152
	ds_read_b64_tr_b16 v[34:35], v0 offset:8768
	ds_read_b64_tr_b16 v[36:37], v0 offset:9856
	ds_read_b64_tr_b16 v[166:167], v0 offset:17472
	ds_read_b64_tr_b16 v[168:169], v0 offset:18560
	ds_read_b64_tr_b16 v[170:171], v0 offset:26176
	ds_read_b64_tr_b16 v[172:173], v0 offset:27264
	s_nop 1
	v_cvt_pk_bf16_f32 v20, v150, v151
	v_cvt_pk_bf16_f32 v21, v152, v153
	global_store_dwordx2 v[18:19], v[20:21], off offset:32 sc1
	s_waitcnt lgkmcnt(6)
	v_mfma_f32_16x16x32_bf16 v[30:33], v[30:33], v[2:5], 0
	s_waitcnt lgkmcnt(4)
	v_mfma_f32_16x16x32_bf16 v[30:33], v[34:37], v[6:9], v[30:33]
	s_waitcnt lgkmcnt(2)
	v_mfma_f32_16x16x32_bf16 v[30:33], v[166:169], v[10:13], v[30:33]
	s_waitcnt lgkmcnt(0)
	v_mfma_f32_16x16x32_bf16 v[30:33], v[170:173], v[14:17], v[30:33]
	ds_read_b64_tr_b16 v[150:151], v0 offset:96
	ds_read_b64_tr_b16 v[152:153], v0 offset:1184
	ds_read_b64_tr_b16 v[154:155], v0 offset:8800
	ds_read_b64_tr_b16 v[156:157], v0 offset:9888
	ds_read_b64_tr_b16 v[158:159], v0 offset:17504
	ds_read_b64_tr_b16 v[160:161], v0 offset:18592
	ds_read_b64_tr_b16 v[162:163], v0 offset:26208
	ds_read_b64_tr_b16 v[164:165], v0 offset:27296
	s_nop 1
	v_cvt_pk_bf16_f32 v20, v30, v31
	v_cvt_pk_bf16_f32 v21, v32, v33
	global_store_dwordx2 v[18:19], v[20:21], off offset:64 sc1
	s_waitcnt lgkmcnt(6)
	v_mfma_f32_16x16x32_bf16 v[150:153], v[150:153], v[2:5], 0
	s_waitcnt lgkmcnt(4)
	v_mfma_f32_16x16x32_bf16 v[150:153], v[154:157], v[6:9], v[150:153]
	s_waitcnt lgkmcnt(2)
	v_mfma_f32_16x16x32_bf16 v[150:153], v[158:161], v[10:13], v[150:153]
	s_waitcnt lgkmcnt(0)
	v_mfma_f32_16x16x32_bf16 v[150:153], v[162:165], v[14:17], v[150:153]
	ds_read_b64_tr_b16 v[30:31], v0 offset:128
	ds_read_b64_tr_b16 v[32:33], v0 offset:1216
	ds_read_b64_tr_b16 v[34:35], v0 offset:8832
	ds_read_b64_tr_b16 v[36:37], v0 offset:9920
	ds_read_b64_tr_b16 v[166:167], v0 offset:17536
	ds_read_b64_tr_b16 v[168:169], v0 offset:18624
	ds_read_b64_tr_b16 v[170:171], v0 offset:26240
	ds_read_b64_tr_b16 v[172:173], v0 offset:27328
	s_nop 1
	v_cvt_pk_bf16_f32 v20, v150, v151
	v_cvt_pk_bf16_f32 v21, v152, v153
	global_store_dwordx2 v[18:19], v[20:21], off offset:96 sc1
	s_waitcnt lgkmcnt(6)
	v_mfma_f32_16x16x32_bf16 v[30:33], v[30:33], v[2:5], 0
	s_waitcnt lgkmcnt(4)
	v_mfma_f32_16x16x32_bf16 v[30:33], v[34:37], v[6:9], v[30:33]
	s_waitcnt lgkmcnt(2)
	v_mfma_f32_16x16x32_bf16 v[30:33], v[166:169], v[10:13], v[30:33]
	s_waitcnt lgkmcnt(0)
	v_mfma_f32_16x16x32_bf16 v[30:33], v[170:173], v[14:17], v[30:33]
	ds_read_b64_tr_b16 v[150:151], v0 offset:160
	ds_read_b64_tr_b16 v[152:153], v0 offset:1248
	ds_read_b64_tr_b16 v[154:155], v0 offset:8864
	ds_read_b64_tr_b16 v[156:157], v0 offset:9952
	ds_read_b64_tr_b16 v[158:159], v0 offset:17568
	ds_read_b64_tr_b16 v[160:161], v0 offset:18656
	ds_read_b64_tr_b16 v[162:163], v0 offset:26272
	ds_read_b64_tr_b16 v[164:165], v0 offset:27360
	s_nop 1
	v_cvt_pk_bf16_f32 v20, v30, v31
	v_cvt_pk_bf16_f32 v21, v32, v33
	global_store_dwordx2 v[18:19], v[20:21], off offset:128 sc1
	s_waitcnt lgkmcnt(6)
	v_mfma_f32_16x16x32_bf16 v[150:153], v[150:153], v[2:5], 0
	s_waitcnt lgkmcnt(4)
	v_mfma_f32_16x16x32_bf16 v[150:153], v[154:157], v[6:9], v[150:153]
	s_waitcnt lgkmcnt(2)
	v_mfma_f32_16x16x32_bf16 v[150:153], v[158:161], v[10:13], v[150:153]
	s_waitcnt lgkmcnt(0)
	v_mfma_f32_16x16x32_bf16 v[150:153], v[162:165], v[14:17], v[150:153]
	ds_read_b64_tr_b16 v[30:31], v0 offset:192
	ds_read_b64_tr_b16 v[32:33], v0 offset:1280
	ds_read_b64_tr_b16 v[34:35], v0 offset:8896
	ds_read_b64_tr_b16 v[36:37], v0 offset:9984
	ds_read_b64_tr_b16 v[166:167], v0 offset:17600
	ds_read_b64_tr_b16 v[168:169], v0 offset:18688
	ds_read_b64_tr_b16 v[170:171], v0 offset:26304
	ds_read_b64_tr_b16 v[172:173], v0 offset:27392
	s_nop 1
	v_cvt_pk_bf16_f32 v20, v150, v151
	v_cvt_pk_bf16_f32 v21, v152, v153
	global_store_dwordx2 v[18:19], v[20:21], off offset:160 sc1
	s_waitcnt lgkmcnt(6)
	v_mfma_f32_16x16x32_bf16 v[30:33], v[30:33], v[2:5], 0
	s_waitcnt lgkmcnt(4)
	v_mfma_f32_16x16x32_bf16 v[30:33], v[34:37], v[6:9], v[30:33]
	s_waitcnt lgkmcnt(2)
	v_mfma_f32_16x16x32_bf16 v[30:33], v[166:169], v[10:13], v[30:33]
	s_waitcnt lgkmcnt(0)
	v_mfma_f32_16x16x32_bf16 v[30:33], v[170:173], v[14:17], v[30:33]
	ds_read_b64_tr_b16 v[150:151], v0 offset:224
	ds_read_b64_tr_b16 v[152:153], v0 offset:1312
	ds_read_b64_tr_b16 v[154:155], v0 offset:8928
	ds_read_b64_tr_b16 v[156:157], v0 offset:10016
	ds_read_b64_tr_b16 v[158:159], v0 offset:17632
	ds_read_b64_tr_b16 v[160:161], v0 offset:18720
	ds_read_b64_tr_b16 v[162:163], v0 offset:26336
	ds_read_b64_tr_b16 v[164:165], v0 offset:27424
	s_nop 1
	v_cvt_pk_bf16_f32 v20, v30, v31
	v_cvt_pk_bf16_f32 v21, v32, v33
	global_store_dwordx2 v[18:19], v[20:21], off offset:192 sc1
	v_add_u32_e32 v0, v0, v26
	s_waitcnt lgkmcnt(6)
	v_mfma_f32_16x16x32_bf16 v[150:153], v[150:153], v[2:5], 0
	s_waitcnt lgkmcnt(4)
	v_mfma_f32_16x16x32_bf16 v[150:153], v[154:157], v[6:9], v[150:153]
	s_waitcnt lgkmcnt(2)
	v_mfma_f32_16x16x32_bf16 v[150:153], v[158:161], v[10:13], v[150:153]
	s_waitcnt lgkmcnt(0)
	v_mfma_f32_16x16x32_bf16 v[150:153], v[162:165], v[14:17], v[150:153]
	s_nop 7
	v_cvt_pk_bf16_f32 v20, v150, v151
	v_cvt_pk_bf16_f32 v21, v152, v153
	global_store_dwordx2 v[18:19], v[20:21], off offset:224 sc1
	ds_read_b64_tr_b16 v[18:19], v0
	ds_read_b64_tr_b16 v[20:21], v0 offset:1088
	v_mov_b64_e32 v[32:33], s[26:27]
	v_mov_b64_e32 v[30:31], s[24:25]
	ds_read_b64_tr_b16 v[34:35], v0 offset:8704
	ds_read_b64_tr_b16 v[36:37], v0 offset:9792
	s_waitcnt lgkmcnt(2)
	v_mfma_f32_16x16x32_bf16 v[18:21], v[18:21], v[30:33], 0
	s_waitcnt lgkmcnt(0)
	v_mfma_f32_16x16x32_bf16 v[18:21], v[34:37], v[30:33], v[18:21]
	ds_read_b64_tr_b16 v[34:35], v0 offset:17408
	ds_read_b64_tr_b16 v[36:37], v0 offset:18496
	s_waitcnt lgkmcnt(0)
	v_mfma_f32_16x16x32_bf16 v[18:21], v[34:37], v[30:33], v[18:21]
	ds_read_b64_tr_b16 v[34:35], v0 offset:26112
	ds_read_b64_tr_b16 v[36:37], v0 offset:27200
	s_waitcnt lgkmcnt(0)
	v_mfma_f32_16x16x32_bf16 v[18:21], v[34:37], v[30:33], v[18:21]
	s_and_saveexec_b64 s[4:5], vcc
	s_cbranch_execz .LBB0_923
	s_lshl_b64 s[8:9], s[6:7], 9
	v_lshl_add_u64 v[30:31], v[22:23], 0, s[8:9]
	s_nop 3
	global_store_dwordx4 v[30:31], v[18:21], off sc1
.LBB0_923:
	s_or_b64 exec, exec, s[4:5]
	v_cmp_eq_u32_e64 s[4:5], 0, v188
	s_and_saveexec_b64 s[8:9], s[4:5]
	s_cbranch_execz .LBB0_925
	s_lshl_b64 s[6:7], s[6:7], 4
	s_add_u32 s6, s37, s6
	s_addc_u32 s7, s60, s7
	v_mov_b32_e32 v103, v105
	global_store_dwordx2 v1, v[102:103], s[6:7] sc1
.LBB0_925:
	s_or_b64 exec, exec, s[8:9]
	v_add3_u32 v0, s34, v27, v28
	ds_read_b64_tr_b16 v[28:29], v0
	ds_read_b64_tr_b16 v[30:31], v0 offset:1088
	ds_read_b64_tr_b16 v[32:33], v0 offset:8704
	ds_read_b64_tr_b16 v[34:35], v0 offset:9792
	s_and_b64 s[6:7], s[56:57], exec
	s_cselect_b32 s6, 1, 19
	s_waitcnt lgkmcnt(2)
	v_mfma_f32_16x16x32_bf16 v[28:31], v[28:31], v[2:5], 0
	s_sub_i32 s7, s10, s30
	s_add_i32 s6, s7, s6
	s_addk_i32 s6, 0x48
	s_waitcnt lgkmcnt(0)
	v_mfma_f32_16x16x32_bf16 v[28:31], v[32:35], v[6:9], v[28:31]
	ds_read_b64_tr_b16 v[32:33], v0 offset:17408
	ds_read_b64_tr_b16 v[34:35], v0 offset:18496
	s_ashr_i32 s7, s6, 31
	s_lshl_b64 s[8:9], s[6:7], 15
	s_waitcnt lgkmcnt(0)
	v_mfma_f32_16x16x32_bf16 v[28:31], v[32:35], v[10:13], v[28:31]
	ds_read_b64_tr_b16 v[32:33], v0 offset:26112
	ds_read_b64_tr_b16 v[34:35], v0 offset:27200
	v_lshl_add_u64 v[18:19], v[24:25], 0, s[8:9]
	s_mov_b32 s25, s24
	s_waitcnt lgkmcnt(0)
	v_mfma_f32_16x16x32_bf16 v[28:31], v[32:35], v[14:17], v[28:31]
	s_mov_b32 s26, s24
	s_mov_b32 s27, s24
	s_nop 5
	v_cvt_pk_bf16_f32 v20, v28, v29
	v_cvt_pk_bf16_f32 v21, v30, v31
	global_store_dwordx2 v[18:19], v[20:21], off sc1
	ds_read_b64_tr_b16 v[28:29], v0 offset:32
	ds_read_b64_tr_b16 v[30:31], v0 offset:1120
	ds_read_b64_tr_b16 v[32:33], v0 offset:8736
	ds_read_b64_tr_b16 v[34:35], v0 offset:9824
	ds_read_b64_tr_b16 v[166:167], v0 offset:17440
	ds_read_b64_tr_b16 v[168:169], v0 offset:18528
	ds_read_b64_tr_b16 v[170:171], v0 offset:26144
	ds_read_b64_tr_b16 v[172:173], v0 offset:27232
	s_waitcnt lgkmcnt(6)
	v_mfma_f32_16x16x32_bf16 v[28:31], v[28:31], v[2:5], 0
	s_waitcnt lgkmcnt(4)
	v_mfma_f32_16x16x32_bf16 v[28:31], v[32:35], v[6:9], v[28:31]
	s_waitcnt lgkmcnt(2)
	v_mfma_f32_16x16x32_bf16 v[28:31], v[166:169], v[10:13], v[28:31]
	s_waitcnt lgkmcnt(0)
	v_mfma_f32_16x16x32_bf16 v[28:31], v[170:173], v[14:17], v[28:31]
	ds_read_b64_tr_b16 v[150:151], v0 offset:64
	ds_read_b64_tr_b16 v[152:153], v0 offset:1152
	ds_read_b64_tr_b16 v[154:155], v0 offset:8768
	ds_read_b64_tr_b16 v[156:157], v0 offset:9856
	ds_read_b64_tr_b16 v[158:159], v0 offset:17472
	ds_read_b64_tr_b16 v[160:161], v0 offset:18560
	ds_read_b64_tr_b16 v[162:163], v0 offset:26176
	ds_read_b64_tr_b16 v[164:165], v0 offset:27264
	s_nop 1
	v_cvt_pk_bf16_f32 v20, v28, v29
	v_cvt_pk_bf16_f32 v21, v30, v31
	global_store_dwordx2 v[18:19], v[20:21], off offset:32 sc1
	s_waitcnt lgkmcnt(6)
	v_mfma_f32_16x16x32_bf16 v[150:153], v[150:153], v[2:5], 0
	s_waitcnt lgkmcnt(4)
	v_mfma_f32_16x16x32_bf16 v[150:153], v[154:157], v[6:9], v[150:153]
	s_waitcnt lgkmcnt(2)
	v_mfma_f32_16x16x32_bf16 v[150:153], v[158:161], v[10:13], v[150:153]
	s_waitcnt lgkmcnt(0)
	v_mfma_f32_16x16x32_bf16 v[150:153], v[162:165], v[14:17], v[150:153]
	ds_read_b64_tr_b16 v[28:29], v0 offset:96
	ds_read_b64_tr_b16 v[30:31], v0 offset:1184
	ds_read_b64_tr_b16 v[32:33], v0 offset:8800
	ds_read_b64_tr_b16 v[34:35], v0 offset:9888
	ds_read_b64_tr_b16 v[166:167], v0 offset:17504
	ds_read_b64_tr_b16 v[168:169], v0 offset:18592
	ds_read_b64_tr_b16 v[170:171], v0 offset:26208
	ds_read_b64_tr_b16 v[172:173], v0 offset:27296
	s_nop 1
	v_cvt_pk_bf16_f32 v20, v150, v151
	v_cvt_pk_bf16_f32 v21, v152, v153
	global_store_dwordx2 v[18:19], v[20:21], off offset:64 sc1
	s_waitcnt lgkmcnt(6)
	v_mfma_f32_16x16x32_bf16 v[28:31], v[28:31], v[2:5], 0
	s_waitcnt lgkmcnt(4)
	v_mfma_f32_16x16x32_bf16 v[28:31], v[32:35], v[6:9], v[28:31]
	s_waitcnt lgkmcnt(2)
	v_mfma_f32_16x16x32_bf16 v[28:31], v[166:169], v[10:13], v[28:31]
	s_waitcnt lgkmcnt(0)
	v_mfma_f32_16x16x32_bf16 v[28:31], v[170:173], v[14:17], v[28:31]
	ds_read_b64_tr_b16 v[150:151], v0 offset:128
	ds_read_b64_tr_b16 v[152:153], v0 offset:1216
	ds_read_b64_tr_b16 v[154:155], v0 offset:8832
	ds_read_b64_tr_b16 v[156:157], v0 offset:9920
	ds_read_b64_tr_b16 v[158:159], v0 offset:17536
	ds_read_b64_tr_b16 v[160:161], v0 offset:18624
	ds_read_b64_tr_b16 v[162:163], v0 offset:26240
	ds_read_b64_tr_b16 v[164:165], v0 offset:27328
	s_nop 1
	v_cvt_pk_bf16_f32 v20, v28, v29
	v_cvt_pk_bf16_f32 v21, v30, v31
	global_store_dwordx2 v[18:19], v[20:21], off offset:96 sc1
	s_waitcnt lgkmcnt(6)
	v_mfma_f32_16x16x32_bf16 v[150:153], v[150:153], v[2:5], 0
	s_waitcnt lgkmcnt(4)
	v_mfma_f32_16x16x32_bf16 v[150:153], v[154:157], v[6:9], v[150:153]
	s_waitcnt lgkmcnt(2)
	v_mfma_f32_16x16x32_bf16 v[150:153], v[158:161], v[10:13], v[150:153]
	s_waitcnt lgkmcnt(0)
	v_mfma_f32_16x16x32_bf16 v[150:153], v[162:165], v[14:17], v[150:153]
	ds_read_b64_tr_b16 v[28:29], v0 offset:160
	ds_read_b64_tr_b16 v[30:31], v0 offset:1248
	ds_read_b64_tr_b16 v[32:33], v0 offset:8864
	ds_read_b64_tr_b16 v[34:35], v0 offset:9952
	ds_read_b64_tr_b16 v[166:167], v0 offset:17568
	ds_read_b64_tr_b16 v[168:169], v0 offset:18656
	ds_read_b64_tr_b16 v[170:171], v0 offset:26272
	ds_read_b64_tr_b16 v[172:173], v0 offset:27360
	s_nop 1
	v_cvt_pk_bf16_f32 v20, v150, v151
	v_cvt_pk_bf16_f32 v21, v152, v153
	global_store_dwordx2 v[18:19], v[20:21], off offset:128 sc1
	s_waitcnt lgkmcnt(6)
	v_mfma_f32_16x16x32_bf16 v[28:31], v[28:31], v[2:5], 0
	s_waitcnt lgkmcnt(4)
	v_mfma_f32_16x16x32_bf16 v[28:31], v[32:35], v[6:9], v[28:31]
	s_waitcnt lgkmcnt(2)
	v_mfma_f32_16x16x32_bf16 v[28:31], v[166:169], v[10:13], v[28:31]
	s_waitcnt lgkmcnt(0)
	v_mfma_f32_16x16x32_bf16 v[28:31], v[170:173], v[14:17], v[28:31]
	ds_read_b64_tr_b16 v[150:151], v0 offset:192
	ds_read_b64_tr_b16 v[152:153], v0 offset:1280
	ds_read_b64_tr_b16 v[154:155], v0 offset:8896
	ds_read_b64_tr_b16 v[156:157], v0 offset:9984
	ds_read_b64_tr_b16 v[158:159], v0 offset:17600
	ds_read_b64_tr_b16 v[160:161], v0 offset:18688
	ds_read_b64_tr_b16 v[162:163], v0 offset:26304
	ds_read_b64_tr_b16 v[164:165], v0 offset:27392
	s_nop 1
	v_cvt_pk_bf16_f32 v20, v28, v29
	v_cvt_pk_bf16_f32 v21, v30, v31
	global_store_dwordx2 v[18:19], v[20:21], off offset:160 sc1
	s_waitcnt lgkmcnt(6)
	v_mfma_f32_16x16x32_bf16 v[150:153], v[150:153], v[2:5], 0
	s_waitcnt lgkmcnt(4)
	v_mfma_f32_16x16x32_bf16 v[150:153], v[154:157], v[6:9], v[150:153]
	s_waitcnt lgkmcnt(2)
	v_mfma_f32_16x16x32_bf16 v[150:153], v[158:161], v[10:13], v[150:153]
	s_waitcnt lgkmcnt(0)
	v_mfma_f32_16x16x32_bf16 v[150:153], v[162:165], v[14:17], v[150:153]
	s_nop 7
	v_cvt_pk_bf16_f32 v20, v150, v151
	v_cvt_pk_bf16_f32 v21, v152, v153
	global_store_dwordx2 v[18:19], v[20:21], off offset:192 sc1
	ds_read_b64_tr_b16 v[28:29], v0 offset:224
	ds_read_b64_tr_b16 v[30:31], v0 offset:1312
	s_waitcnt lgkmcnt(0)
	v_mfma_f32_16x16x32_bf16 v[2:5], v[28:31], v[2:5], 0
	ds_read_b64_tr_b16 v[28:29], v0 offset:8928
	ds_read_b64_tr_b16 v[30:31], v0 offset:10016
	s_waitcnt lgkmcnt(0)
	v_mfma_f32_16x16x32_bf16 v[2:5], v[28:31], v[6:9], v[2:5]
	ds_read_b64_tr_b16 v[6:7], v0 offset:17632
	ds_read_b64_tr_b16 v[8:9], v0 offset:18720
	s_waitcnt lgkmcnt(0)
	v_mfma_f32_16x16x32_bf16 v[2:5], v[6:9], v[10:13], v[2:5]
	ds_read_b64_tr_b16 v[6:7], v0 offset:26336
	ds_read_b64_tr_b16 v[8:9], v0 offset:27424
	v_add_u32_e32 v0, v0, v26
	s_waitcnt lgkmcnt(0)
	v_mfma_f32_16x16x32_bf16 v[2:5], v[6:9], v[14:17], v[2:5]
	v_mov_b64_e32 v[6:7], s[24:25]
	v_mov_b64_e32 v[8:9], s[26:27]
	s_nop 5
	v_cvt_pk_bf16_f32 v2, v2, v3
	v_cvt_pk_bf16_f32 v3, v4, v5
	global_store_dwordx2 v[18:19], v[2:3], off offset:224 sc1
	ds_read_b64_tr_b16 v[2:3], v0
	ds_read_b64_tr_b16 v[4:5], v0 offset:1088
	ds_read_b64_tr_b16 v[10:11], v0 offset:8704
	ds_read_b64_tr_b16 v[12:13], v0 offset:9792
	s_waitcnt lgkmcnt(2)
	v_mfma_f32_16x16x32_bf16 v[2:5], v[2:5], v[6:9], 0
	s_waitcnt lgkmcnt(0)
	v_mfma_f32_16x16x32_bf16 v[2:5], v[10:13], v[6:9], v[2:5]
	ds_read_b64_tr_b16 v[10:11], v0 offset:17408
	ds_read_b64_tr_b16 v[12:13], v0 offset:18496
	s_waitcnt lgkmcnt(0)
	v_mfma_f32_16x16x32_bf16 v[2:5], v[10:13], v[6:9], v[2:5]
	ds_read_b64_tr_b16 v[10:11], v0 offset:26112
	ds_read_b64_tr_b16 v[12:13], v0 offset:27200
	s_waitcnt lgkmcnt(0)
	v_mfma_f32_16x16x32_bf16 v[2:5], v[10:13], v[6:9], v[2:5]
	s_and_saveexec_b64 s[8:9], vcc
	s_cbranch_execz .LBB0_927
	s_lshl_b64 s[10:11], s[6:7], 9
	v_lshl_add_u64 v[6:7], v[22:23], 0, s[10:11]
	s_nop 3
	global_store_dwordx4 v[6:7], v[2:5], off sc1
.LBB0_927:
	s_or_b64 exec, exec, s[8:9]
	s_and_saveexec_b64 s[8:9], s[4:5]
	s_cbranch_execz .LBB0_929
	s_lshl_b64 s[4:5], s[6:7], 4
	s_add_u32 s4, s37, s4
	s_addc_u32 s5, s60, s5
	v_mov_b32_e32 v99, v101
	global_store_dwordx2 v1, v[98:99], s[4:5] sc1
.LBB0_929:
	s_or_b64 exec, exec, s[8:9]
	s_waitcnt vmcnt(0) lgkmcnt(0)
	s_barrier
	s_cmp_lg_u32 s3, 0
	s_cbranch_scc1 .Lw5_skip
	s_mov_b64 s[98:99], exec
	s_mov_b64 exec, 1
	global_atomic_add v1, v215, s[78:79] offset:2560
	s_mov_b64 exec, s[98:99]
.Lw5_skip:
	s_mov_b32 s8, 4

.LBB0_1058:
	s_or_b64 exec, exec, s[0:1]
	s_mov_b64 s[0:1], s[76:77]
	s_mov_b32 s4, s3
	s_mov_b32 s5, -1
	s_waitcnt lgkmcnt(0)
	s_barrier
	s_cmp_lg_u32 s3, 0
	s_cbranch_scc1 .Lw5_bar
	s_load_dwordx2 s[98:99], s[76:77], 0xb8
	s_movk_i32 vcc_lo, 0x480
	v_readlane_b32 vcc_hi, v255, 26
	s_cmp_eq_u32 vcc_hi, -1
	s_cselect_b32 vcc_lo, 0x240, vcc_lo
	v_mov_b32_e32 v0, 0
	s_mov_b32 m0, 0
	s_waitcnt lgkmcnt(0)
.Lw5_spin:
	global_load_dword v70, v0, s[98:99] offset:2560 sc1
	s_waitcnt vmcnt(0)
	v_readfirstlane_b32 vcc_hi, v70
	s_cmp_ge_u32 vcc_hi, vcc_lo
	s_cbranch_scc1 .Lw5_done
	s_add_u32 m0, m0, 1
	s_cmp_gt_u32 m0, 0x100000
	s_cbranch_scc1 .Lw5_done
	s_sleep 1
	s_branch .Lw5_spin

.Lw5_bar:
	s_barrier
	s_nop 0
	v_mbcnt_lo_u32_b32 v0, s5, 0
	v_mbcnt_hi_u32_b32 v0, s5, v0
	v_lshl_add_u32 v70, s4, 6, v0
	v_readlane_b32 s4, v255, 4
	v_readlane_b32 s5, v255, 5
	s_andn2_b64 vcc, exec, s[4:5]
	s_cbranch_vccnz .LBB0_1167
	s_load_dwordx2 s[0:1], s[0:1], 0xb8
	v_lshlrev_b32_e32 v72, 3, v70
	s_movk_i32 s4, 0x80
	v_cmp_gt_i32_e64 s[4:5], s4, v70
	v_ashrrev_i32_e32 v71, 31, v70
	s_waitcnt lgkmcnt(0)
	s_add_u32 s12, s0, 0x12400000
	s_addc_u32 s13, s1, 0
	s_add_u32 s16, s0, 0x3e0000
	s_addc_u32 s17, s1, 0
	s_add_u32 s18, s0, 0x340000
	v_ashrrev_i32_e32 v73, 31, v72
	s_addc_u32 s19, s1, 0
	s_mov_b32 s25, s2
	s_branch .LBB0_1061
